# mod and bias prologues: the 18 vector loads of each thread issued together (one memory round trip instead of 9-18)
# baseline (speedup 1.0000x reference)
; __device__ __forceinline__ void bias_phase(const Params& p, char* smem, int tid, int bid) {
;     ...
;     __syncthreads();
;     for (int i = tid; i < 9 * 1024; i += NTHR) { const int r = i >> 10, k = i & 1023; sL[i] = mod[(size_t)(l * 9 + r) * 6144 + which * 3072 + k]; }
;     __syncthreads();
.LBB0_824:
	s_barrier
	s_and_saveexec_b64 s[0:1], s[4:5]
	s_cbranch_execz .LBB0_834
	s_mul_i32 s18, s29, 0xc00
	s_mov_b32 s19, s17
	s_lshl_b64 s[18:19], s[18:19], 2
	v_readlane_b32 s20, v253, 11
	v_readlane_b32 s21, v253, 12
	s_add_u32 s18, s20, s18
	s_mul_i32 s34, s30, 9
	s_addc_u32 s19, s21, s19
	s_mul_i32 s20, s34, 0x6000
	s_add_u32 s18, s18, s20
	s_addc_u32 s19, s19, 0
	global_load_dword v50, v43, s[18:19]
	global_load_dword v51, v43, s[18:19] offset:2048
	s_add_u32 s18, s18, 0x6000
	s_addc_u32 s19, s19, 0
	global_load_dword v52, v43, s[18:19]
	global_load_dword v53, v43, s[18:19] offset:2048
	s_add_u32 s18, s18, 0x6000
	s_addc_u32 s19, s19, 0
	global_load_dword v54, v43, s[18:19]
	global_load_dword v55, v43, s[18:19] offset:2048
	s_add_u32 s18, s18, 0x6000
	s_addc_u32 s19, s19, 0
	global_load_dword v56, v43, s[18:19]
	global_load_dword v57, v43, s[18:19] offset:2048
	s_add_u32 s18, s18, 0x6000
	s_addc_u32 s19, s19, 0
	global_load_dword v58, v43, s[18:19]
	global_load_dword v59, v43, s[18:19] offset:2048
	s_add_u32 s18, s18, 0x6000
	s_addc_u32 s19, s19, 0
	global_load_dword v60, v43, s[18:19]
	global_load_dword v61, v43, s[18:19] offset:2048
	s_add_u32 s18, s18, 0x6000
	s_addc_u32 s19, s19, 0
	global_load_dword v62, v43, s[18:19]
	global_load_dword v63, v43, s[18:19] offset:2048
	s_add_u32 s18, s18, 0x6000
	s_addc_u32 s19, s19, 0
	global_load_dword v64, v43, s[18:19]
	global_load_dword v65, v43, s[18:19] offset:2048
	s_add_u32 s18, s18, 0x6000
	s_addc_u32 s19, s19, 0
	global_load_dword v66, v43, s[18:19]
	global_load_dword v67, v43, s[18:19] offset:2048
	s_add_u32 s18, s18, 0x6000
	s_addc_u32 s19, s19, 0
	s_waitcnt vmcnt(17)
	ds_write_b32 v44, v50 offset:0
	s_waitcnt vmcnt(16)
	ds_write_b32 v44, v51 offset:2048
	s_waitcnt vmcnt(15)
	ds_write_b32 v44, v52 offset:4096
	s_waitcnt vmcnt(14)
	ds_write_b32 v44, v53 offset:6144
	s_waitcnt vmcnt(13)
	ds_write_b32 v44, v54 offset:8192
	s_waitcnt vmcnt(12)
	ds_write_b32 v44, v55 offset:10240
	s_waitcnt vmcnt(11)
	ds_write_b32 v44, v56 offset:12288
	s_waitcnt vmcnt(10)
	ds_write_b32 v44, v57 offset:14336
	s_waitcnt vmcnt(9)
	ds_write_b32 v44, v58 offset:16384
	s_waitcnt vmcnt(8)
	ds_write_b32 v44, v59 offset:18432
	s_waitcnt vmcnt(7)
	ds_write_b32 v44, v60 offset:20480
	s_waitcnt vmcnt(6)
	ds_write_b32 v44, v61 offset:22528
	s_waitcnt vmcnt(5)
	ds_write_b32 v44, v62 offset:24576
	s_waitcnt vmcnt(4)
	ds_write_b32 v44, v63 offset:26624
	s_waitcnt vmcnt(3)
	ds_write_b32 v44, v64 offset:28672
	s_waitcnt vmcnt(2)
	ds_write_b32 v44, v65 offset:30720
	s_waitcnt vmcnt(1)
	ds_write_b32 v44, v66 offset:32768
	s_waitcnt vmcnt(0)
	ds_write_b32 v44, v67 offset:34816

; __device__ __forceinline__ void mod_phase(const Params& p, char* smem, int tid, int bid) {
;     ...
;   for (int i = tid; i < 9 * 1024; i += NTHR) {
;     float v = i < 8192 ? p.in[1][i] : p.in[3][i - 8192];
;     sL[i] = v / (1.f + __expf(-v));
;   }
.LBB0_844:
	s_and_b64 vcc, exec, s[0:1]
	s_cbranch_vccz .LBB0_865
	s_cmpk_gt_i32 s62, 0xbf
	s_cbranch_scc1 .LBB0_865
	s_movk_i32 s0, 0x23ff
	v_cmp_lt_i32_e32 vcc, s0, v208
	v_lshlrev_b32_e32 v6, 2, v208
	s_and_saveexec_b64 s[0:1], vcc
	s_xor_b64 s[0:1], exec, s[0:1]
	v_lshlrev_b32_e32 v6, 2, v208
	s_or_saveexec_b64 s[0:1], s[0:1]
	s_movk_i32 s8, 0x2000
	s_xor_b64 exec, exec, s[0:1]
	s_cbranch_execz .LBB0_852
	v_readlane_b32 s36, v254, 43
	v_ashrrev_i32_e32 v209, 31, v208
	v_readlane_b32 s38, v254, 45
	v_readlane_b32 s39, v254, 46
	v_add_u32_e32 v2, 0, v6
	v_readlane_b32 s42, v254, 49
	v_readlane_b32 s43, v254, 50
	s_waitcnt lgkmcnt(0)
	v_lshl_add_u64 v[0:1], v[208:209], 2, s[38:39]
	s_mov_b64 s[4:5], 0
	v_mov_b32_e32 v200, v208
	v_readlane_b32 s37, v254, 44
	v_readlane_b32 s40, v254, 47
	v_readlane_b32 s41, v254, 48
	v_readlane_b32 s44, v254, 51
	v_readlane_b32 s45, v254, 52
	v_readlane_b32 s46, v254, 53
	v_readlane_b32 s47, v254, 54
	v_readlane_b32 s48, v254, 55
	v_readlane_b32 s49, v254, 56
	v_readlane_b32 s50, v254, 57
	v_readlane_b32 s51, v254, 58
	s_mov_b32 s6, s38
	s_mov_b32 s7, s39
	global_load_dword v12, v6, s[6:7]
	s_add_u32 s6, s6, 0x800
	s_addc_u32 s7, s7, 0
	global_load_dword v13, v6, s[6:7]
	s_add_u32 s6, s6, 0x800
	s_addc_u32 s7, s7, 0
	global_load_dword v14, v6, s[6:7]
	s_add_u32 s6, s6, 0x800
	s_addc_u32 s7, s7, 0
	global_load_dword v15, v6, s[6:7]
	s_add_u32 s6, s6, 0x800
	s_addc_u32 s7, s7, 0
	global_load_dword v16, v6, s[6:7]
	s_add_u32 s6, s6, 0x800
	s_addc_u32 s7, s7, 0
	global_load_dword v17, v6, s[6:7]
	s_add_u32 s6, s6, 0x800
	s_addc_u32 s7, s7, 0
	global_load_dword v18, v6, s[6:7]
	s_add_u32 s6, s6, 0x800
	s_addc_u32 s7, s7, 0
	global_load_dword v19, v6, s[6:7]
	s_add_u32 s6, s6, 0x800
	s_addc_u32 s7, s7, 0
	global_load_dword v20, v6, s[6:7]
	s_add_u32 s6, s6, 0x800
	s_addc_u32 s7, s7, 0
	global_load_dword v21, v6, s[6:7]
	s_add_u32 s6, s6, 0x800
	s_addc_u32 s7, s7, 0
	global_load_dword v22, v6, s[6:7]
	s_add_u32 s6, s6, 0x800
	s_addc_u32 s7, s7, 0
	global_load_dword v23, v6, s[6:7]
	s_add_u32 s6, s6, 0x800
	s_addc_u32 s7, s7, 0
	global_load_dword v24, v6, s[6:7]
	s_add_u32 s6, s6, 0x800
	s_addc_u32 s7, s7, 0
	global_load_dword v25, v6, s[6:7]
	s_add_u32 s6, s6, 0x800
	s_addc_u32 s7, s7, 0
	global_load_dword v26, v6, s[6:7]
	s_add_u32 s6, s6, 0x800
	s_addc_u32 s7, s7, 0
	global_load_dword v27, v6, s[6:7]
	s_add_u32 s6, s6, 0x800
	s_addc_u32 s7, s7, 0
	s_mov_b32 s6, s42
	s_mov_b32 s7, s43
	global_load_dword v28, v6, s[6:7]
	s_add_u32 s6, s6, 0x800
	s_addc_u32 s7, s7, 0
	global_load_dword v29, v6, s[6:7]
	s_add_u32 s6, s6, 0x800
	s_addc_u32 s7, s7, 0
	s_waitcnt vmcnt(17)
	v_mul_f32_e32 v4, 0xbfb8aa3b, v12
	v_exp_f32_e32 v4, v4
	s_nop 0
	v_add_f32_e32 v4, 1.0, v4
	v_div_scale_f32 v5, s[6:7], v4, v4, v12
	v_rcp_f32_e32 v7, v5
	v_div_scale_f32 v8, vcc, v12, v4, v12
	v_fma_f32 v9, -v5, v7, 1.0
	v_fmac_f32_e32 v7, v9, v7
	v_mul_f32_e32 v9, v8, v7
	v_fma_f32 v10, -v5, v9, v8
	v_fmac_f32_e32 v9, v10, v7
	v_fma_f32 v5, -v5, v9, v8
	v_div_fmas_f32 v5, v5, v7, v9
	v_div_fixup_f32 v3, v5, v4, v12
	ds_write_b32 v2, v3 offset:0
	s_waitcnt vmcnt(16)
	v_mul_f32_e32 v4, 0xbfb8aa3b, v13
	v_exp_f32_e32 v4, v4
	s_nop 0
	v_add_f32_e32 v4, 1.0, v4
	v_div_scale_f32 v5, s[6:7], v4, v4, v13
	v_rcp_f32_e32 v7, v5
	v_div_scale_f32 v8, vcc, v13, v4, v13
	v_fma_f32 v9, -v5, v7, 1.0
	v_fmac_f32_e32 v7, v9, v7
	v_mul_f32_e32 v9, v8, v7
	v_fma_f32 v10, -v5, v9, v8
	v_fmac_f32_e32 v9, v10, v7
	v_fma_f32 v5, -v5, v9, v8
	v_div_fmas_f32 v5, v5, v7, v9
	v_div_fixup_f32 v3, v5, v4, v13
	ds_write_b32 v2, v3 offset:2048
	s_waitcnt vmcnt(15)
	v_mul_f32_e32 v4, 0xbfb8aa3b, v14
	v_exp_f32_e32 v4, v4
	s_nop 0
	v_add_f32_e32 v4, 1.0, v4
	v_div_scale_f32 v5, s[6:7], v4, v4, v14
	v_rcp_f32_e32 v7, v5
	v_div_scale_f32 v8, vcc, v14, v4, v14
	v_fma_f32 v9, -v5, v7, 1.0
	v_fmac_f32_e32 v7, v9, v7
	v_mul_f32_e32 v9, v8, v7
	v_fma_f32 v10, -v5, v9, v8
	v_fmac_f32_e32 v9, v10, v7
	v_fma_f32 v5, -v5, v9, v8
	v_div_fmas_f32 v5, v5, v7, v9
	v_div_fixup_f32 v3, v5, v4, v14
	ds_write_b32 v2, v3 offset:4096
	s_waitcnt vmcnt(14)
	v_mul_f32_e32 v4, 0xbfb8aa3b, v15
	v_exp_f32_e32 v4, v4
	s_nop 0
	v_add_f32_e32 v4, 1.0, v4
	v_div_scale_f32 v5, s[6:7], v4, v4, v15
	v_rcp_f32_e32 v7, v5
	v_div_scale_f32 v8, vcc, v15, v4, v15
	v_fma_f32 v9, -v5, v7, 1.0
	v_fmac_f32_e32 v7, v9, v7
	v_mul_f32_e32 v9, v8, v7
	v_fma_f32 v10, -v5, v9, v8
	v_fmac_f32_e32 v9, v10, v7
	v_fma_f32 v5, -v5, v9, v8
	v_div_fmas_f32 v5, v5, v7, v9
	v_div_fixup_f32 v3, v5, v4, v15
	ds_write_b32 v2, v3 offset:6144
	s_waitcnt vmcnt(13)
	v_mul_f32_e32 v4, 0xbfb8aa3b, v16
	v_exp_f32_e32 v4, v4
	s_nop 0
	v_add_f32_e32 v4, 1.0, v4
	v_div_scale_f32 v5, s[6:7], v4, v4, v16
	v_rcp_f32_e32 v7, v5
	v_div_scale_f32 v8, vcc, v16, v4, v16
	v_fma_f32 v9, -v5, v7, 1.0
	v_fmac_f32_e32 v7, v9, v7
	v_mul_f32_e32 v9, v8, v7
	v_fma_f32 v10, -v5, v9, v8
	v_fmac_f32_e32 v9, v10, v7
	v_fma_f32 v5, -v5, v9, v8
	v_div_fmas_f32 v5, v5, v7, v9
	v_div_fixup_f32 v3, v5, v4, v16
	ds_write_b32 v2, v3 offset:8192
	s_waitcnt vmcnt(12)
	v_mul_f32_e32 v4, 0xbfb8aa3b, v17
	v_exp_f32_e32 v4, v4
	s_nop 0
	v_add_f32_e32 v4, 1.0, v4
	v_div_scale_f32 v5, s[6:7], v4, v4, v17
	v_rcp_f32_e32 v7, v5
	v_div_scale_f32 v8, vcc, v17, v4, v17
	v_fma_f32 v9, -v5, v7, 1.0
	v_fmac_f32_e32 v7, v9, v7
	v_mul_f32_e32 v9, v8, v7
	v_fma_f32 v10, -v5, v9, v8
	v_fmac_f32_e32 v9, v10, v7
	v_fma_f32 v5, -v5, v9, v8
	v_div_fmas_f32 v5, v5, v7, v9
	v_div_fixup_f32 v3, v5, v4, v17
	ds_write_b32 v2, v3 offset:10240
	s_waitcnt vmcnt(11)
; __device__ __forceinline__ void mod_phase(const Params& p, char* smem, int tid, int bid) {
;     ...
;   for (int i = tid; i < 9 * 1024; i += NTHR) {
;     float v = i < 8192 ? p.in[1][i] : p.in[3][i - 8192];
;     sL[i] = v / (1.f + __expf(-v));
;   }
	v_mul_f32_e32 v4, 0xbfb8aa3b, v18
	v_exp_f32_e32 v4, v4
	s_nop 0
	v_add_f32_e32 v4, 1.0, v4
	v_div_scale_f32 v5, s[6:7], v4, v4, v18
	v_rcp_f32_e32 v7, v5
	v_div_scale_f32 v8, vcc, v18, v4, v18
	v_fma_f32 v9, -v5, v7, 1.0
	v_fmac_f32_e32 v7, v9, v7
	v_mul_f32_e32 v9, v8, v7
	v_fma_f32 v10, -v5, v9, v8
	v_fmac_f32_e32 v9, v10, v7
	v_fma_f32 v5, -v5, v9, v8
	v_div_fmas_f32 v5, v5, v7, v9
	v_div_fixup_f32 v3, v5, v4, v18
	ds_write_b32 v2, v3 offset:12288
	s_waitcnt vmcnt(10)
	v_mul_f32_e32 v4, 0xbfb8aa3b, v19
	v_exp_f32_e32 v4, v4
	s_nop 0
	v_add_f32_e32 v4, 1.0, v4
	v_div_scale_f32 v5, s[6:7], v4, v4, v19
	v_rcp_f32_e32 v7, v5
	v_div_scale_f32 v8, vcc, v19, v4, v19
	v_fma_f32 v9, -v5, v7, 1.0
	v_fmac_f32_e32 v7, v9, v7
	v_mul_f32_e32 v9, v8, v7
	v_fma_f32 v10, -v5, v9, v8
	v_fmac_f32_e32 v9, v10, v7
	v_fma_f32 v5, -v5, v9, v8
	v_div_fmas_f32 v5, v5, v7, v9
	v_div_fixup_f32 v3, v5, v4, v19
	ds_write_b32 v2, v3 offset:14336
	s_waitcnt vmcnt(9)
	v_mul_f32_e32 v4, 0xbfb8aa3b, v20
	v_exp_f32_e32 v4, v4
	s_nop 0
	v_add_f32_e32 v4, 1.0, v4
	v_div_scale_f32 v5, s[6:7], v4, v4, v20
	v_rcp_f32_e32 v7, v5
	v_div_scale_f32 v8, vcc, v20, v4, v20
	v_fma_f32 v9, -v5, v7, 1.0
	v_fmac_f32_e32 v7, v9, v7
	v_mul_f32_e32 v9, v8, v7
	v_fma_f32 v10, -v5, v9, v8
	v_fmac_f32_e32 v9, v10, v7
	v_fma_f32 v5, -v5, v9, v8
	v_div_fmas_f32 v5, v5, v7, v9
	v_div_fixup_f32 v3, v5, v4, v20
	ds_write_b32 v2, v3 offset:16384
	s_waitcnt vmcnt(8)
	v_mul_f32_e32 v4, 0xbfb8aa3b, v21
	v_exp_f32_e32 v4, v4
	s_nop 0
	v_add_f32_e32 v4, 1.0, v4
	v_div_scale_f32 v5, s[6:7], v4, v4, v21
	v_rcp_f32_e32 v7, v5
	v_div_scale_f32 v8, vcc, v21, v4, v21
	v_fma_f32 v9, -v5, v7, 1.0
	v_fmac_f32_e32 v7, v9, v7
	v_mul_f32_e32 v9, v8, v7
	v_fma_f32 v10, -v5, v9, v8
	v_fmac_f32_e32 v9, v10, v7
	v_fma_f32 v5, -v5, v9, v8
	v_div_fmas_f32 v5, v5, v7, v9
	v_div_fixup_f32 v3, v5, v4, v21
	ds_write_b32 v2, v3 offset:18432
	s_waitcnt vmcnt(7)
	v_mul_f32_e32 v4, 0xbfb8aa3b, v22
	v_exp_f32_e32 v4, v4
	s_nop 0
	v_add_f32_e32 v4, 1.0, v4
	v_div_scale_f32 v5, s[6:7], v4, v4, v22
	v_rcp_f32_e32 v7, v5
	v_div_scale_f32 v8, vcc, v22, v4, v22
	v_fma_f32 v9, -v5, v7, 1.0
	v_fmac_f32_e32 v7, v9, v7
	v_mul_f32_e32 v9, v8, v7
	v_fma_f32 v10, -v5, v9, v8
	v_fmac_f32_e32 v9, v10, v7
	v_fma_f32 v5, -v5, v9, v8
	v_div_fmas_f32 v5, v5, v7, v9
	v_div_fixup_f32 v3, v5, v4, v22
	ds_write_b32 v2, v3 offset:20480
	s_waitcnt vmcnt(6)
	v_mul_f32_e32 v4, 0xbfb8aa3b, v23
	v_exp_f32_e32 v4, v4
	s_nop 0
	v_add_f32_e32 v4, 1.0, v4
	v_div_scale_f32 v5, s[6:7], v4, v4, v23
	v_rcp_f32_e32 v7, v5
	v_div_scale_f32 v8, vcc, v23, v4, v23
	v_fma_f32 v9, -v5, v7, 1.0
	v_fmac_f32_e32 v7, v9, v7
	v_mul_f32_e32 v9, v8, v7
	v_fma_f32 v10, -v5, v9, v8
	v_fmac_f32_e32 v9, v10, v7
	v_fma_f32 v5, -v5, v9, v8
	v_div_fmas_f32 v5, v5, v7, v9
	v_div_fixup_f32 v3, v5, v4, v23
	ds_write_b32 v2, v3 offset:22528
	s_waitcnt vmcnt(5)
	v_mul_f32_e32 v4, 0xbfb8aa3b, v24
	v_exp_f32_e32 v4, v4
	s_nop 0
	v_add_f32_e32 v4, 1.0, v4
	v_div_scale_f32 v5, s[6:7], v4, v4, v24
	v_rcp_f32_e32 v7, v5
	v_div_scale_f32 v8, vcc, v24, v4, v24
	v_fma_f32 v9, -v5, v7, 1.0
	v_fmac_f32_e32 v7, v9, v7
	v_mul_f32_e32 v9, v8, v7
	v_fma_f32 v10, -v5, v9, v8
	v_fmac_f32_e32 v9, v10, v7
	v_fma_f32 v5, -v5, v9, v8
	v_div_fmas_f32 v5, v5, v7, v9
	v_div_fixup_f32 v3, v5, v4, v24
	ds_write_b32 v2, v3 offset:24576
	s_waitcnt vmcnt(4)
	v_mul_f32_e32 v4, 0xbfb8aa3b, v25
	v_exp_f32_e32 v4, v4
	s_nop 0
	v_add_f32_e32 v4, 1.0, v4
	v_div_scale_f32 v5, s[6:7], v4, v4, v25
	v_rcp_f32_e32 v7, v5
	v_div_scale_f32 v8, vcc, v25, v4, v25
	v_fma_f32 v9, -v5, v7, 1.0
	v_fmac_f32_e32 v7, v9, v7
	v_mul_f32_e32 v9, v8, v7
	v_fma_f32 v10, -v5, v9, v8
	v_fmac_f32_e32 v9, v10, v7
	v_fma_f32 v5, -v5, v9, v8
	v_div_fmas_f32 v5, v5, v7, v9
	v_div_fixup_f32 v3, v5, v4, v25
	ds_write_b32 v2, v3 offset:26624
	s_waitcnt vmcnt(3)
	v_mul_f32_e32 v4, 0xbfb8aa3b, v26
	v_exp_f32_e32 v4, v4
	s_nop 0
	v_add_f32_e32 v4, 1.0, v4
	v_div_scale_f32 v5, s[6:7], v4, v4, v26
	v_rcp_f32_e32 v7, v5
	v_div_scale_f32 v8, vcc, v26, v4, v26
	v_fma_f32 v9, -v5, v7, 1.0
	v_fmac_f32_e32 v7, v9, v7
	v_mul_f32_e32 v9, v8, v7
	v_fma_f32 v10, -v5, v9, v8
	v_fmac_f32_e32 v9, v10, v7
	v_fma_f32 v5, -v5, v9, v8
	v_div_fmas_f32 v5, v5, v7, v9
	v_div_fixup_f32 v3, v5, v4, v26
	ds_write_b32 v2, v3 offset:28672
	s_waitcnt vmcnt(2)
	v_mul_f32_e32 v4, 0xbfb8aa3b, v27
	v_exp_f32_e32 v4, v4
	s_nop 0
	v_add_f32_e32 v4, 1.0, v4
	v_div_scale_f32 v5, s[6:7], v4, v4, v27
	v_rcp_f32_e32 v7, v5
	v_div_scale_f32 v8, vcc, v27, v4, v27
	v_fma_f32 v9, -v5, v7, 1.0
	v_fmac_f32_e32 v7, v9, v7
	v_mul_f32_e32 v9, v8, v7
	v_fma_f32 v10, -v5, v9, v8
	v_fmac_f32_e32 v9, v10, v7
	v_fma_f32 v5, -v5, v9, v8
	v_div_fmas_f32 v5, v5, v7, v9
	v_div_fixup_f32 v3, v5, v4, v27
	ds_write_b32 v2, v3 offset:30720
	s_waitcnt vmcnt(1)
	v_mul_f32_e32 v4, 0xbfb8aa3b, v28
	v_exp_f32_e32 v4, v4
	s_nop 0
	v_add_f32_e32 v4, 1.0, v4
	v_div_scale_f32 v5, s[6:7], v4, v4, v28
	v_rcp_f32_e32 v7, v5
	v_div_scale_f32 v8, vcc, v28, v4, v28
	v_fma_f32 v9, -v5, v7, 1.0
	v_fmac_f32_e32 v7, v9, v7
	v_mul_f32_e32 v9, v8, v7
	v_fma_f32 v10, -v5, v9, v8
	v_fmac_f32_e32 v9, v10, v7
	v_fma_f32 v5, -v5, v9, v8
	v_div_fmas_f32 v5, v5, v7, v9
	v_div_fixup_f32 v3, v5, v4, v28
	ds_write_b32 v2, v3 offset:32768
	s_waitcnt vmcnt(0)
	v_mul_f32_e32 v4, 0xbfb8aa3b, v29
	v_exp_f32_e32 v4, v4
	s_nop 0
	v_add_f32_e32 v4, 1.0, v4
	v_div_scale_f32 v5, s[6:7], v4, v4, v29
	v_rcp_f32_e32 v7, v5
	v_div_scale_f32 v8, vcc, v29, v4, v29
	v_fma_f32 v9, -v5, v7, 1.0
	v_fmac_f32_e32 v7, v9, v7
	v_mul_f32_e32 v9, v8, v7
	v_fma_f32 v10, -v5, v9, v8
	v_fmac_f32_e32 v9, v10, v7
	v_fma_f32 v5, -v5, v9, v8
	v_div_fmas_f32 v5, v5, v7, v9
	v_div_fixup_f32 v3, v5, v4, v29
	ds_write_b32 v2, v3 offset:34816
	s_or_b64 exec, exec, s[4:5]
